# FoX item prologue: cum[k] load no longer drained with vmcnt(0) on wave 0 (prologue de-serialisation)
# baseline (speedup 1.0000x reference)
; #define ATT_ISSUE(j_) do { ATT_ISSUE_K(j_); ATT_ISSUE_V(j_); } while (0)
;     ...
;     const int lane = tid & 63, wv = tid >> 6, r = lane & 31, h2 = lane >> 5;
;     const int q0 = qt * 256 + wv * 32;
;     bf16x8 qf[KS];
; #pragma unroll
;     for (int ks = 0; ks < KS; ++ks) qf[ks] = *(const bf16x8*)(Q + (size_t)(q0 + r) * ldq + 16 * ks + 8 * h2);
;     f32x16 oacc[4];
; #pragma unroll
;     for (int d = 0; d < 4; ++d) for (int i = 0; i < 16; ++i) oacc[d][i] = 0.f;
;     float l_run = 0.f;
;     const float c0 = (DECAY ? cum[q0 + r] * LOG2E : 0.f) - m0;
;     const int ntiles = (qt + 1) * 4;
;     u32x4 pk_[NKL], pv_[2]; float pc_ = 0.f;
;     ...
;     __syncthreads();
;     ATT_ISSUE(0);
.LBB0_244:
	s_and_b64 vcc, exec, s[0:1]
	s_cbranch_vccz .LBB0_303
	s_add_i32 s0, s54, -4
	s_lshr_b32 s55, s0, 3
	s_lshl_b32 s1, s52, 3
	s_and_b32 s0, s0, 6
	s_or_b32 s57, s0, s1
	s_sub_i32 s56, 15, s55
	s_bfe_u32 s53, s57, 0x20001
	s_bitcmp1_b32 s24, 0
	s_cselect_b64 s[24:25], -1, 0
	v_ashrrev_i32_e32 v0, 1, v196
	s_lshl_b32 s14, s52, 12
	s_mov_b32 s15, s5
	s_mov_b64 s[0:1], -1
	s_and_b64 vcc, exec, s[24:25]
	v_and_b32_e32 v181, 0xffffffe0, v0
	s_cbranch_vccz .LBB0_289
	v_lshlrev_b32_e32 v214, 2, v196
	v_add_u32_e32 v214, 0x1c000, v214
	ds_write_b32 v214, v223 offset:0
	ds_write_b32 v214, v224 offset:2048
	ds_write_b32 v214, v225 offset:4096
	ds_write_b32 v214, v240 offset:6144
	ds_write_b32 v214, v241 offset:8192
	ds_write_b32 v214, v242 offset:10240
	ds_write_b32 v214, v243 offset:12288
	ds_write_b32 v214, v244 offset:14336
	ds_write_b32 v214, v245 offset:16384
	ds_write_b32 v214, v246 offset:18432
	s_lshr_b32 s4, s57, 1
	s_mul_i32 s1, s14, 0x2780
	s_mul_hi_u32 s0, s14, 0x2780
	s_add_u32 s1, s30, s1
	s_addc_u32 s0, s31, s0
	s_lshl_b32 s12, s53, 8
	s_add_u32 s1, s1, s12
	s_addc_u32 s12, s0, 0
	s_add_u32 s34, s1, 0x1b80
	s_addc_u32 s35, s12, 0
	s_add_u32 s0, s1, 0x1f80
	s_addc_u32 s1, s12, 0
	s_lshl_b32 s12, s4, 14
	v_readlane_b32 s24, v252, 20
	s_add_u32 s24, s24, s12
	v_readlane_b32 s12, v252, 21
	s_addc_u32 s25, s12, 0
	v_readlane_b32 s12, v254, 7
	v_and_b32_e32 v6, 31, v196
	v_lshl_add_u32 v200, s56, 8, v181
	v_mov_b32_e32 v0, s12
	v_ashrrev_i32_e32 v197, 31, v196
	ds_read_b32 v7, v0
	v_or_b32_e32 v160, v200, v6
	v_mov_b64_e32 v[2:3], s[34:35]
	v_lshrrev_b32_e32 v0, 28, v197
	v_mad_i64_i32 v[2:3], s[34:35], v160, s3, v[2:3]
	v_mov_b32_e32 v199, v1
	v_add_u32_e32 v0, v196, v0
	v_ashrrev_i32_e32 v161, 31, v160
	v_lshl_add_u64 v[2:3], v[2:3], 0, v[198:199]
	v_ashrrev_i32_e32 v8, 4, v0
	v_and_b32_e32 v0, -16, v0
	global_load_dwordx4 v[140:143], v[2:3], off
	global_load_dwordx4 v[136:139], v[2:3], off offset:32
	global_load_dwordx4 v[132:135], v[2:3], off offset:64
	global_load_dwordx4 v[128:131], v[2:3], off offset:96
	global_load_dwordx4 v[124:127], v[2:3], off offset:128
	global_load_dwordx4 v[120:123], v[2:3], off offset:160
	global_load_dwordx4 v[116:119], v[2:3], off offset:192
	global_load_dwordx4 v[112:115], v[2:3], off offset:224
	v_lshl_add_u64 v[2:3], v[160:161], 2, s[24:25]
	v_sub_u32_e32 v11, v196, v0
	global_load_dword v9, v[2:3], off
	v_mov_b64_e32 v[4:5], s[0:1]
	v_lshlrev_b32_e32 v2, 3, v11
	v_mad_i64_i32 v[12:13], s[34:35], v8, s3, v[4:5]
	v_ashrrev_i32_e32 v3, 31, v2
	v_lshl_add_u64 v[14:15], v[2:3], 1, v[12:13]
	v_add_u32_e32 v13, 0x200, v196
	v_ashrrev_i32_e32 v0, 31, v13
	v_lshrrev_b32_e32 v0, 28, v0
	v_add_u32_e32 v0, v13, v0
	v_ashrrev_i32_e32 v10, 4, v0
	v_and_b32_e32 v0, -16, v0
	v_sub_u32_e32 v12, v13, v0
	v_mad_i64_i32 v[16:17], s[34:35], v10, s3, v[4:5]
	v_lshlrev_b32_e32 v4, 3, v12
	v_ashrrev_i32_e32 v5, 31, v4
	s_waitcnt lgkmcnt(0)
	s_barrier
	v_lshl_add_u64 v[16:17], v[4:5], 1, v[16:17]
	global_load_dwordx4 v[214:217], v[14:15], off
	global_load_dwordx4 v[222:225], v[16:17], off
	v_cmp_gt_i32_e32 vcc, 64, v196
	v_mov_b32_e32 v183, 0
	v_mov_b32_e32 v201, 0
	s_and_saveexec_b64 s[34:35], vcc
	s_cbranch_execz .LBB0_248
	v_lshl_add_u64 v[14:15], v[196:197], 2, s[24:25]
	global_load_dword v201, v[14:15], off
